# v34_p0tail
# baseline (speedup 1.0000x reference)
; __device__ __forceinline__ unsigned cvt_pk_bf16(float lo, float hi) { unsigned r; asm volatile("v_cvt_pk_bf16_f32 %0, %1, %2" : "=v"(r) : "v"(lo), "v"(hi)); return r; }
; __device__ __forceinline__ void phase0(const Params& p, LAS unsigned char* lds, int gw, int NGW, int wave, int lane, int G) {
;     ...
;       for (int row = gw; row < MT; row += NGW) {
;           const f32x4* xr = (const f32x4*)(x + (size_t)row * DM) + lane; f32x4 v[16]; float ss = 0.f;
;           const f32x4* gp = (const f32x4*)g + lane; asm volatile("" : "+v"(gp), "+v"(xr));
; #pragma unroll
;           for (int j = 0; j < 16; ++j) { v[j] = xr[64 * j]; ss += (v[j][0] * v[j][0] + v[j][1] * v[j][1]) + (v[j][2] * v[j][2] + v[j][3] * v[j][3]); }
;           const float rs = rsqrtf(wave_sum(ss) * (1.f / DM) + EPSN);
;           u32x2* o = (u32x2*)(A0 + (size_t)row * DM) + lane; unsigned* o8 = (unsigned*)(ws + WS_SC + (size_t)row * DM) + lane;
; #pragma unroll
;           for (int j = 0; j < 16; ++j) { const f32x4 gg = gp[64 * j]; const f32x4 a = v[j] * rs * gg; u32x2 w; w.x = cvt_pk_bf16(a[0], a[1]); w.y = cvt_pk_bf16(a[2], a[3]); o[64 * j] = w;
.LBB0_29:
	v_cmp_lt_i32_e32 vcc, v83, v82
	v_lshl_add_u64 v[2:3], s[58:59], 0, v[66:67]
	v_mov_b64_e32 v[0:1], v[70:71]
	v_cndmask_b32_e32 v6, v79, v83, vcc
	v_cmp_lt_i32_e32 vcc, v84, v82
	v_mov_b64_e32 v[72:73], v[64:65]
	flat_load_dwordx4 v[60:63], v[0:1] nt
	flat_load_dwordx4 v[56:59], v[0:1] offset:1024 nt
	flat_load_dwordx4 v[48:51], v[0:1] offset:2048 nt
	flat_load_dwordx4 v[40:43], v[0:1] offset:3072 nt
	v_cndmask_b32_e32 v7, v79, v84, vcc
	v_cmp_lt_i32_e32 vcc, v85, v82
	v_lshl_add_u64 v[4:5], s[58:59], 0, v[68:69]
	v_lshlrev_b32_e32 v137, 2, v6
	v_cndmask_b32_e32 v8, v79, v85, vcc
	v_cmp_lt_i32_e32 vcc, v86, v82
	v_lshlrev_b32_e32 v138, 2, v7
	v_lshlrev_b32_e32 v139, 2, v8
	v_cndmask_b32_e32 v9, v79, v86, vcc
	v_cmp_lt_i32_e32 vcc, v87, v82
	v_lshlrev_b32_e32 v140, 2, v9
	v_mov_b32_e32 v135, 0
	v_cndmask_b32_e32 v10, v79, v87, vcc
	v_cmp_lt_i32_e32 vcc, v88, v82
	v_lshlrev_b32_e32 v141, 2, v10
	v_mov_b32_e32 v136, 0
	v_cndmask_b32_e32 v11, v79, v88, vcc
	v_add_co_u32_e32 v80, vcc, s15, v2
	v_lshlrev_b32_e32 v142, 2, v11
	s_nop 0
	v_addc_co_u32_e32 v81, vcc, 0, v3, vcc
	v_add_co_u32_e32 v74, vcc, s17, v2
	s_add_i32 s30, s30, s60
	s_nop 0
	v_addc_co_u32_e32 v75, vcc, 0, v3, vcc
	v_add_co_u32_e32 v76, vcc, s16, v4
	v_lshl_add_u64 v[66:67], v[66:67], 0, s[4:5]
	s_nop 0
	v_addc_co_u32_e32 v77, vcc, 0, v5, vcc
	v_add_co_u32_e32 v2, vcc, s3, v0
	v_lshl_add_u64 v[68:69], v[68:69], 0, s[6:7]
	s_nop 0
	v_addc_co_u32_e32 v3, vcc, 0, v1, vcc
	v_add_co_u32_e32 v4, vcc, s8, v0
	v_lshl_add_u64 v[70:71], v[70:71], 0, s[10:11]
	s_nop 0
	v_addc_co_u32_e32 v5, vcc, 0, v1, vcc
	v_add_co_u32_e32 v6, vcc, s9, v0
	s_cmpk_gt_i32 s30, 0x1fff
	s_nop 0
	v_addc_co_u32_e32 v7, vcc, 0, v1, vcc
	v_add_co_u32_e32 v228, vcc, 0x2000, v72
	s_nop 1
	v_addc_co_u32_e32 v229, vcc, 0, v73, vcc
	v_add_co_u32_e32 v230, vcc, 0x4000, v72
	s_nop 1
	v_addc_co_u32_e32 v231, vcc, 0, v73, vcc
	flat_load_dwordx4 v[90:93], v[72:73]
	global_load_dwordx4 v[164:167], v[72:73], off offset:1024
	global_load_dwordx4 v[168:171], v[72:73], off offset:2048
	global_load_dwordx4 v[172:175], v[72:73], off offset:3072
	global_load_dwordx4 v[176:179], v[228:229], off offset:-4096
	global_load_dwordx4 v[180:183], v[228:229], off offset:-3072
	global_load_dwordx4 v[184:187], v[228:229], off offset:-2048
	global_load_dwordx4 v[188:191], v[228:229], off offset:-1024
	global_load_dwordx4 v[192:195], v[228:229], off
	global_load_dwordx4 v[196:199], v[228:229], off offset:1024
	global_load_dwordx4 v[200:203], v[228:229], off offset:2048
	global_load_dwordx4 v[204:207], v[228:229], off offset:3072
	global_load_dwordx4 v[208:211], v[230:231], off offset:-4096
	global_load_dwordx4 v[212:215], v[230:231], off offset:-3072
	global_load_dwordx4 v[216:219], v[230:231], off offset:-2048
	global_load_dwordx4 v[220:223], v[230:231], off offset:-1024
	flat_load_dwordx4 v[52:55], v[2:3] nt
	flat_load_dwordx4 v[32:35], v[2:3] offset:3072 nt
	flat_load_dwordx4 v[20:23], v[4:5] offset:2048 nt
	flat_load_dwordx4 v[8:11], v[6:7] offset:1024 nt
	flat_load_dwordx4 v[36:39], v[2:3] offset:2048 nt
	flat_load_dwordx4 v[44:47], v[2:3] offset:1024 nt
	flat_load_dwordx4 v[24:27], v[4:5] offset:1024 nt
	flat_load_dwordx4 v[28:31], v[4:5] nt
	flat_load_dwordx4 v[12:15], v[6:7] nt
	flat_load_dwordx4 v[16:19], v[4:5] offset:3072 nt
	s_nop 0
	flat_load_dwordx4 v[0:3], v[6:7] offset:3072 nt
	s_nop 0
	flat_load_dwordx4 v[4:7], v[6:7] offset:2048 nt
	s_waitcnt vmcnt(0) lgkmcnt(0)
	v_pk_mul_f32 v[94:95], v[62:63], v[62:63]
	v_pk_mul_f32 v[96:97], v[60:61], v[60:61]
	v_pk_mul_f32 v[98:99], v[58:59], v[58:59]
	v_pk_mul_f32 v[100:101], v[56:57], v[56:57]
	v_pk_mov_b32 v[104:105], v[96:97], v[94:95] op_sel:[1,0]
	v_mov_b32_e32 v97, v95
	v_pk_mov_b32 v[94:95], v[100:101], v[98:99] op_sel:[1,0]
	v_mov_b32_e32 v101, v99
	v_mul_f32_e32 v78, v49, v49
	v_mul_f32_e32 v102, v51, v51
	v_pk_add_f32 v[96:97], v[104:105], v[96:97]
	v_pk_add_f32 v[94:95], v[94:95], v[100:101]
	v_mul_f32_e32 v123, v42, v42
	v_mul_f32_e32 v125, v43, v43
	v_mul_f32_e32 v143, v40, v40
	v_mul_f32_e32 v144, v41, v41
	v_pk_fma_f32 v[120:121], v[48:49], v[48:49], v[78:79] op_sel_hi:[1,1,0]
	v_pk_fma_f32 v[102:103], v[50:51], v[50:51], v[102:103] op_sel_hi:[1,1,0]
	v_pk_add_f32 v[96:97], v[96:97], v[96:97] op_sel:[0,1] op_sel_hi:[1,0]
	v_pk_add_f32 v[94:95], v[94:95], v[94:95] op_sel:[0,1] op_sel_hi:[1,0]
	v_mov_b32_e32 v121, v123
	v_mov_b32_e32 v103, v125
	v_mov_b32_e32 v97, v143
	v_mov_b32_e32 v95, v144
	v_pk_add_f32 v[102:103], v[120:121], v[102:103]
	v_pk_add_f32 v[94:95], v[96:97], v[94:95]
	v_pk_mul_f32 v[98:99], v[54:55], v[54:55]
	v_pk_mul_f32 v[106:107], v[52:53], v[52:53]
	v_pk_mul_f32 v[108:109], v[34:35], v[34:35]
	v_pk_mov_b32 v[100:101], v[106:107], v[98:99] op_sel:[1,0]
	v_mov_b32_e32 v107, v99
	v_pk_mul_f32 v[110:111], v[32:33], v[32:33]
	v_pk_mul_f32 v[112:113], v[22:23], v[22:23]
	v_pk_mul_f32 v[114:115], v[20:21], v[20:21]
	v_pk_mul_f32 v[116:117], v[10:11], v[10:11]
	v_pk_mul_f32 v[118:119], v[8:9], v[8:9]
	v_mul_f32_e32 v78, v45, v45
	v_mul_f32_e32 v122, v47, v47
	v_pk_add_f32 v[100:101], v[100:101], v[106:107]
	v_pk_add_f32 v[94:95], v[94:95], v[102:103]
	v_mul_f32_e32 v145, v38, v38
	v_mul_f32_e32 v146, v39, v39
	v_mul_f32_e32 v153, v36, v36
	v_mul_f32_e32 v154, v37, v37
	v_pk_mov_b32 v[98:99], v[110:111], v[108:109] op_sel:[1,0]
	v_mov_b32_e32 v111, v109
	v_pk_mov_b32 v[104:105], v[114:115], v[112:113] op_sel:[1,0]
	v_mov_b32_e32 v115, v113
	v_pk_mov_b32 v[108:109], v[118:119], v[116:117] op_sel:[1,0]
	v_mov_b32_e32 v119, v117
	v_pk_fma_f32 v[112:113], v[44:45], v[44:45], v[78:79] op_sel_hi:[1,1,0]
	v_pk_fma_f32 v[116:117], v[46:47], v[46:47], v[122:123] op_sel_hi:[1,1,0]
; __device__ __forceinline__ unsigned cvt_pk_bf16(float lo, float hi) { unsigned r; asm volatile("v_cvt_pk_bf16_f32 %0, %1, %2" : "=v"(r) : "v"(lo), "v"(hi)); return r; }
; __device__ __forceinline__ float wave_sum(float v) {
; #pragma unroll
;     for (int o = 1; o < 64; o <<= 1) v += __shfl_xor(v, o);
;     return v;
; __device__ __forceinline__ void phase0(const Params& p, LAS unsigned char* lds, int gw, int NGW, int wave, int lane, int G) {
;     ...
;           for (int j = 0; j < 16; ++j) { v[j] = xr[64 * j]; ss += (v[j][0] * v[j][0] + v[j][1] * v[j][1]) + (v[j][2] * v[j][2] + v[j][3] * v[j][3]); }
;           const float rs = rsqrtf(wave_sum(ss) * (1.f / DM) + EPSN);
;           u32x2* o = (u32x2*)(A0 + (size_t)row * DM) + lane; unsigned* o8 = (unsigned*)(ws + WS_SC + (size_t)row * DM) + lane;
; #pragma unroll
;           for (int j = 0; j < 16; ++j) { const f32x4 gg = gp[64 * j]; const f32x4 a = v[j] * rs * gg; u32x2 w; w.x = cvt_pk_bf16(a[0], a[1]); w.y = cvt_pk_bf16(a[2], a[3]); o[64 * j] = w;
;               int q = __builtin_amdgcn_cvt_pk_fp8_f32(a[0] * 16.f, a[1] * 16.f, 0, false); q = __builtin_amdgcn_cvt_pk_fp8_f32(a[2] * 16.f, a[3] * 16.f, q, true); o8[64 * j] = (unsigned)q; }
	v_pk_add_f32 v[100:101], v[100:101], v[100:101] op_sel:[0,1] op_sel_hi:[1,0]
	v_pk_add_f32 v[94:95], v[94:95], v[94:95] op_sel:[0,1] op_sel_hi:[1,0]
	v_mov_b32_e32 v113, v145
	v_mov_b32_e32 v117, v146
	v_mov_b32_e32 v101, v154
	v_mov_b32_e32 v95, v153
	v_pk_add_f32 v[106:107], v[108:109], v[118:119]
	v_pk_add_f32 v[108:109], v[112:113], v[116:117]
	v_pk_add_f32 v[94:95], v[94:95], v[100:101]
	v_mul_f32_e32 v124, v29, v29
	v_mul_f32_e32 v126, v31, v31
	v_pk_add_f32 v[98:99], v[98:99], v[110:111]
	v_pk_add_f32 v[94:95], v[94:95], v[108:109]
	v_mul_f32_e32 v147, v26, v26
	v_mul_f32_e32 v148, v27, v27
	v_mul_f32_e32 v155, v24, v24
	v_mul_f32_e32 v156, v25, v25
	v_pk_fma_f32 v[122:123], v[28:29], v[28:29], v[124:125] op_sel_hi:[1,1,0]
	v_pk_fma_f32 v[124:125], v[30:31], v[30:31], v[126:127] op_sel_hi:[1,1,0]
	v_pk_add_f32 v[98:99], v[98:99], v[98:99] op_sel:[0,1] op_sel_hi:[1,0]
	v_pk_add_f32 v[94:95], v[94:95], v[94:95] op_sel:[0,1] op_sel_hi:[1,0]
	v_mov_b32_e32 v123, v147
	v_mov_b32_e32 v125, v148
	v_mov_b32_e32 v99, v156
	v_mov_b32_e32 v95, v155
	v_pk_add_f32 v[110:111], v[122:123], v[124:125]
	v_pk_add_f32 v[94:95], v[94:95], v[98:99]
	v_mul_f32_e32 v128, v17, v17
	v_mul_f32_e32 v130, v19, v19
	v_pk_add_f32 v[104:105], v[104:105], v[114:115]
	v_pk_add_f32 v[94:95], v[94:95], v[110:111]
	v_mul_f32_e32 v149, v14, v14
	v_mul_f32_e32 v150, v15, v15
	v_mul_f32_e32 v157, v12, v12
	v_mul_f32_e32 v158, v13, v13
	v_pk_fma_f32 v[126:127], v[16:17], v[16:17], v[128:129] op_sel_hi:[1,1,0]
	v_pk_fma_f32 v[128:129], v[18:19], v[18:19], v[130:131] op_sel_hi:[1,1,0]
	v_pk_add_f32 v[104:105], v[104:105], v[104:105] op_sel:[0,1] op_sel_hi:[1,0]
	v_pk_add_f32 v[94:95], v[94:95], v[94:95] op_sel:[0,1] op_sel_hi:[1,0]
	v_mov_b32_e32 v127, v149
	v_mov_b32_e32 v129, v150
	v_mov_b32_e32 v105, v158
	v_mov_b32_e32 v95, v157
	v_pk_add_f32 v[112:113], v[126:127], v[128:129]
	v_pk_add_f32 v[94:95], v[94:95], v[104:105]
	v_mul_f32_e32 v132, v5, v5
	v_mul_f32_e32 v134, v7, v7
	v_pk_add_f32 v[94:95], v[94:95], v[112:113]
	v_mul_f32_e32 v151, v2, v2
	v_mul_f32_e32 v152, v3, v3
	v_mul_f32_e32 v159, v0, v0
	v_mul_f32_e32 v160, v1, v1
	v_pk_fma_f32 v[130:131], v[4:5], v[4:5], v[132:133] op_sel_hi:[1,1,0]
	v_pk_fma_f32 v[132:133], v[6:7], v[6:7], v[134:135] op_sel_hi:[1,1,0]
	v_pk_add_f32 v[106:107], v[106:107], v[106:107] op_sel:[0,1] op_sel_hi:[1,0]
	v_pk_add_f32 v[94:95], v[94:95], v[94:95] op_sel:[0,1] op_sel_hi:[1,0]
	v_mov_b32_e32 v131, v151
	v_mov_b32_e32 v133, v152
	v_mov_b32_e32 v107, v160
	v_mov_b32_e32 v95, v159
	v_pk_add_f32 v[114:115], v[130:131], v[132:133]
	v_pk_add_f32 v[94:95], v[94:95], v[106:107]
	s_nop 0
	v_pk_add_f32 v[94:95], v[94:95], v[114:115]
	s_nop 0
	v_add_f32_e32 v78, v94, v95
	ds_bpermute_b32 v94, v137, v78
	s_waitcnt lgkmcnt(0)
	v_add_f32_e32 v78, v78, v94
	ds_bpermute_b32 v94, v138, v78
	s_waitcnt lgkmcnt(0)
	v_add_f32_e32 v78, v78, v94
	ds_bpermute_b32 v94, v139, v78
	s_waitcnt lgkmcnt(0)
	v_add_f32_e32 v78, v78, v94
	ds_bpermute_b32 v94, v140, v78
	s_waitcnt lgkmcnt(0)
	v_add_f32_e32 v78, v78, v94
	ds_bpermute_b32 v94, v141, v78
	s_waitcnt lgkmcnt(0)
	v_add_f32_e32 v78, v78, v94
	ds_bpermute_b32 v94, v142, v78
	s_waitcnt lgkmcnt(0)
	v_add_f32_e32 v78, v78, v94
	v_fmamk_f32 v78, v78, 0x39800000, v89
	v_mul_f32_e32 v94, 0x4b800000, v78
	v_cmp_gt_f32_e32 vcc, s14, v78
	s_nop 1
	v_cndmask_b32_e32 v78, v78, v94, vcc
	v_rsq_f32_e32 v78, v78
	s_nop 0
	v_mul_f32_e32 v94, 0x45800000, v78
	v_cndmask_b32_e32 v78, v78, v94, vcc
	v_pk_mul_f32 v[60:61], v[60:61], v[78:79] op_sel_hi:[1,0]
	v_pk_mul_f32 v[96:97], v[58:59], v[78:79] op_sel_hi:[1,0]
	v_pk_mul_f32 v[58:59], v[90:91], v[60:61]
	v_pk_mul_f32 v[62:63], v[62:63], v[78:79] op_sel_hi:[1,0]
	v_cvt_pk_bf16_f32 v60, v58, v59
	v_mul_f32_e32 v58, 0x41800000, v58
	v_mul_f32_e32 v59, 0x41800000, v59
	v_cvt_pk_fp8_f32 v135, v58, v59
	v_pk_mul_f32 v[94:95], v[56:57], v[78:79] op_sel_hi:[1,0]
	v_pk_mul_f32 v[56:57], v[92:93], v[62:63]
	v_pk_mul_f32 v[48:49], v[48:49], v[78:79] op_sel_hi:[1,0]
	v_cvt_pk_bf16_f32 v61, v56, v57
	v_mul_f32_e32 v56, 0x41800000, v56
	v_mul_f32_e32 v57, 0x41800000, v57
	v_cvt_pk_fp8_f32 v135, v56, v57 op_sel:[0,0,1]
	global_store_dwordx2 v[74:75], v[60:61], off offset:-4096
	v_pk_mul_f32 v[50:51], v[50:51], v[78:79] op_sel_hi:[1,0]
	v_pk_mul_f32 v[40:41], v[40:41], v[78:79] op_sel_hi:[1,0]
	global_store_dword v[76:77], v135, off
	v_mov_b64_e32 v[56:57], v[164:165]
	v_mov_b64_e32 v[58:59], v[166:167]
	v_pk_mul_f32 v[42:43], v[42:43], v[78:79] op_sel_hi:[1,0]
	v_pk_mul_f32 v[44:45], v[44:45], v[78:79] op_sel_hi:[1,0]
	v_pk_mul_f32 v[46:47], v[46:47], v[78:79] op_sel_hi:[1,0]
	v_pk_mul_f32 v[36:37], v[36:37], v[78:79] op_sel_hi:[1,0]
	v_pk_mul_f32 v[38:39], v[38:39], v[78:79] op_sel_hi:[1,0]
	v_pk_mul_f32 v[32:33], v[32:33], v[78:79] op_sel_hi:[1,0]
	v_pk_mul_f32 v[34:35], v[34:35], v[78:79] op_sel_hi:[1,0]
	v_pk_mul_f32 v[28:29], v[28:29], v[78:79] op_sel_hi:[1,0]
	v_pk_mul_f32 v[30:31], v[30:31], v[78:79] op_sel_hi:[1,0]
	v_pk_mul_f32 v[24:25], v[24:25], v[78:79] op_sel_hi:[1,0]
	v_pk_mul_f32 v[26:27], v[26:27], v[78:79] op_sel_hi:[1,0]
	v_pk_mul_f32 v[20:21], v[20:21], v[78:79] op_sel_hi:[1,0]
	v_pk_mul_f32 v[22:23], v[22:23], v[78:79] op_sel_hi:[1,0]
	v_pk_mul_f32 v[16:17], v[16:17], v[78:79] op_sel_hi:[1,0]
	v_pk_mul_f32 v[18:19], v[18:19], v[78:79] op_sel_hi:[1,0]
	v_pk_mul_f32 v[12:13], v[12:13], v[78:79] op_sel_hi:[1,0]
	v_pk_mul_f32 v[14:15], v[14:15], v[78:79] op_sel_hi:[1,0]
	v_pk_mul_f32 v[8:9], v[8:9], v[78:79] op_sel_hi:[1,0]
	v_pk_mul_f32 v[10:11], v[10:11], v[78:79] op_sel_hi:[1,0]
	v_pk_mul_f32 v[4:5], v[4:5], v[78:79] op_sel_hi:[1,0]
	v_pk_mul_f32 v[6:7], v[6:7], v[78:79] op_sel_hi:[1,0]
; __device__ __forceinline__ unsigned cvt_pk_bf16(float lo, float hi) { unsigned r; asm volatile("v_cvt_pk_bf16_f32 %0, %1, %2" : "=v"(r) : "v"(lo), "v"(hi)); return r; }
; __device__ __forceinline__ void phase0(const Params& p, LAS unsigned char* lds, int gw, int NGW, int wave, int lane, int G) {
;     ...
;           for (int j = 0; j < 16; ++j) { const f32x4 gg = gp[64 * j]; const f32x4 a = v[j] * rs * gg; u32x2 w; w.x = cvt_pk_bf16(a[0], a[1]); w.y = cvt_pk_bf16(a[2], a[3]); o[64 * j] = w;
;               int q = __builtin_amdgcn_cvt_pk_fp8_f32(a[0] * 16.f, a[1] * 16.f, 0, false); q = __builtin_amdgcn_cvt_pk_fp8_f32(a[2] * 16.f, a[3] * 16.f, q, true); o8[64 * j] = (unsigned)q; }
	v_pk_mul_f32 v[0:1], v[0:1], v[78:79] op_sel_hi:[1,0]
	v_pk_mul_f32 v[2:3], v[2:3], v[78:79] op_sel_hi:[1,0]
	v_pk_mul_f32 v[56:57], v[56:57], v[94:95]
	s_nop 0
	v_cvt_pk_bf16_f32 v60, v56, v57
	v_mul_f32_e32 v56, 0x41800000, v56
	v_mul_f32_e32 v57, 0x41800000, v57
	v_cvt_pk_fp8_f32 v136, v56, v57
	v_pk_mul_f32 v[58:59], v[58:59], v[96:97]
	s_nop 0
	v_cvt_pk_bf16_f32 v61, v58, v59
	v_mul_f32_e32 v58, 0x41800000, v58
	v_mul_f32_e32 v59, 0x41800000, v59
	v_cvt_pk_fp8_f32 v136, v58, v59 op_sel:[0,0,1]
	global_store_dwordx2 v[80:81], v[60:61], off offset:512
	v_mov_b32_e32 v60, 0
	global_store_dword v[76:77], v136, off offset:256
	v_mov_b64_e32 v[56:57], v[168:169]
	v_mov_b64_e32 v[58:59], v[170:171]
	v_pk_mul_f32 v[48:49], v[48:49], v[56:57]
	s_nop 0
	v_cvt_pk_bf16_f32 v56, v48, v49
	v_mul_f32_e32 v48, 0x41800000, v48
	v_mul_f32_e32 v49, 0x41800000, v49
	v_cvt_pk_fp8_f32 v60, v48, v49
	v_pk_mul_f32 v[50:51], v[50:51], v[58:59]
	v_mov_b32_e32 v58, 0
	v_cvt_pk_bf16_f32 v57, v50, v51
	v_mul_f32_e32 v50, 0x41800000, v50
	v_mul_f32_e32 v51, 0x41800000, v51
	v_cvt_pk_fp8_f32 v60, v50, v51 op_sel:[0,0,1]
	global_store_dwordx2 v[80:81], v[56:57], off offset:1024
	v_add_co_u32_e32 v56, vcc, s3, v72
	global_store_dword v[76:77], v60, off offset:512
	v_mov_b64_e32 v[48:49], v[172:173]
	v_mov_b64_e32 v[50:51], v[174:175]
	v_addc_co_u32_e32 v57, vcc, 0, v73, vcc
	v_pk_mul_f32 v[40:41], v[40:41], v[48:49]
	s_nop 0
	v_cvt_pk_bf16_f32 v48, v40, v41
	v_mul_f32_e32 v40, 0x41800000, v40
	v_mul_f32_e32 v41, 0x41800000, v41
	v_cvt_pk_fp8_f32 v58, v40, v41
	v_pk_mul_f32 v[42:43], v[42:43], v[50:51]
	v_pk_mul_f32 v[50:51], v[54:55], v[78:79] op_sel_hi:[1,0]
	v_cvt_pk_bf16_f32 v49, v42, v43
	v_mul_f32_e32 v42, 0x41800000, v42
	v_mul_f32_e32 v43, 0x41800000, v43
	v_cvt_pk_fp8_f32 v58, v42, v43 op_sel:[0,0,1]
	global_store_dwordx2 v[80:81], v[48:49], off offset:1536
	v_pk_mul_f32 v[48:49], v[52:53], v[78:79] op_sel_hi:[1,0]
	global_store_dword v[76:77], v58, off offset:768
	v_mov_b64_e32 v[40:41], v[176:177]
	v_mov_b64_e32 v[42:43], v[178:179]
	v_mov_b32_e32 v58, 0
	v_pk_mul_f32 v[40:41], v[48:49], v[40:41]
	s_nop 0
	v_cvt_pk_bf16_f32 v48, v40, v41
	v_mul_f32_e32 v40, 0x41800000, v40
	v_mul_f32_e32 v41, 0x41800000, v41
	v_cvt_pk_fp8_f32 v58, v40, v41
	v_pk_mul_f32 v[42:43], v[50:51], v[42:43]
	s_nop 0
	v_cvt_pk_bf16_f32 v49, v42, v43
	v_mul_f32_e32 v42, 0x41800000, v42
	v_mul_f32_e32 v43, 0x41800000, v43
	v_cvt_pk_fp8_f32 v58, v42, v43 op_sel:[0,0,1]
	global_store_dwordx2 v[80:81], v[48:49], off offset:2048
	v_mov_b32_e32 v48, 0
	global_store_dword v[76:77], v58, off offset:1024
	v_mov_b64_e32 v[40:41], v[180:181]
	v_mov_b64_e32 v[42:43], v[182:183]
	v_pk_mul_f32 v[40:41], v[44:45], v[40:41]
	s_nop 0
	v_cvt_pk_bf16_f32 v44, v40, v41
	v_mul_f32_e32 v40, 0x41800000, v40
	v_mul_f32_e32 v41, 0x41800000, v41
	v_cvt_pk_fp8_f32 v48, v40, v41
	v_pk_mul_f32 v[42:43], v[46:47], v[42:43]
	s_nop 0
	v_cvt_pk_bf16_f32 v45, v42, v43
	v_mul_f32_e32 v42, 0x41800000, v42
	v_mul_f32_e32 v43, 0x41800000, v43
	v_cvt_pk_fp8_f32 v48, v42, v43 op_sel:[0,0,1]
	global_store_dwordx2 v[80:81], v[44:45], off offset:2560
	v_mov_b32_e32 v44, 0
	global_store_dword v[76:77], v48, off offset:1280
	v_mov_b64_e32 v[40:41], v[184:185]
	v_mov_b64_e32 v[42:43], v[186:187]
	v_pk_mul_f32 v[36:37], v[36:37], v[40:41]
	s_nop 0
	v_cvt_pk_bf16_f32 v40, v36, v37
	v_mul_f32_e32 v36, 0x41800000, v36
	v_mul_f32_e32 v37, 0x41800000, v37
	v_cvt_pk_fp8_f32 v44, v36, v37
	v_pk_mul_f32 v[38:39], v[38:39], v[42:43]
	v_mov_b32_e32 v42, 0
	v_cvt_pk_bf16_f32 v41, v38, v39
	v_mul_f32_e32 v38, 0x41800000, v38
	v_mul_f32_e32 v39, 0x41800000, v39
	v_cvt_pk_fp8_f32 v44, v38, v39 op_sel:[0,0,1]
	global_store_dwordx2 v[80:81], v[40:41], off offset:3072
	v_add_co_u32_e32 v40, vcc, s8, v72
	global_store_dword v[76:77], v44, off offset:1536
	v_mov_b64_e32 v[36:37], v[188:189]
	v_mov_b64_e32 v[38:39], v[190:191]
	v_addc_co_u32_e32 v41, vcc, 0, v73, vcc
	v_pk_mul_f32 v[32:33], v[32:33], v[36:37]
	s_nop 0
	v_cvt_pk_bf16_f32 v36, v32, v33
	v_mul_f32_e32 v32, 0x41800000, v32
	v_mul_f32_e32 v33, 0x41800000, v33
	v_cvt_pk_fp8_f32 v42, v32, v33
	v_pk_mul_f32 v[34:35], v[34:35], v[38:39]
	s_nop 0
	v_cvt_pk_bf16_f32 v37, v34, v35
	v_mul_f32_e32 v34, 0x41800000, v34
	v_mul_f32_e32 v35, 0x41800000, v35
	v_cvt_pk_fp8_f32 v42, v34, v35 op_sel:[0,0,1]
	global_store_dwordx2 v[80:81], v[36:37], off offset:3584
	v_mov_b32_e32 v36, 0
	global_store_dword v[76:77], v42, off offset:1792
	v_mov_b64_e32 v[32:33], v[192:193]
	v_mov_b64_e32 v[34:35], v[194:195]
	v_pk_mul_f32 v[28:29], v[28:29], v[32:33]
	s_nop 0
	v_cvt_pk_bf16_f32 v32, v28, v29
; __device__ __forceinline__ unsigned cvt_pk_bf16(float lo, float hi) { unsigned r; asm volatile("v_cvt_pk_bf16_f32 %0, %1, %2" : "=v"(r) : "v"(lo), "v"(hi)); return r; }
; __device__ __forceinline__ void phase0(const Params& p, LAS unsigned char* lds, int gw, int NGW, int wave, int lane, int G) {
;     ...
;           for (int j = 0; j < 16; ++j) { const f32x4 gg = gp[64 * j]; const f32x4 a = v[j] * rs * gg; u32x2 w; w.x = cvt_pk_bf16(a[0], a[1]); w.y = cvt_pk_bf16(a[2], a[3]); o[64 * j] = w;
;               int q = __builtin_amdgcn_cvt_pk_fp8_f32(a[0] * 16.f, a[1] * 16.f, 0, false); q = __builtin_amdgcn_cvt_pk_fp8_f32(a[2] * 16.f, a[3] * 16.f, q, true); o8[64 * j] = (unsigned)q; }
;       } }
	v_mul_f32_e32 v28, 0x41800000, v28
	v_mul_f32_e32 v29, 0x41800000, v29
	v_cvt_pk_fp8_f32 v36, v28, v29
	v_pk_mul_f32 v[30:31], v[30:31], v[34:35]
	s_nop 0
	v_cvt_pk_bf16_f32 v33, v30, v31
	v_mul_f32_e32 v30, 0x41800000, v30
	v_mul_f32_e32 v31, 0x41800000, v31
	v_cvt_pk_fp8_f32 v36, v30, v31 op_sel:[0,0,1]
	global_store_dwordx2 v[74:75], v[32:33], off
	v_mov_b32_e32 v32, 0
	global_store_dword v[76:77], v36, off offset:2048
	v_mov_b64_e32 v[28:29], v[196:197]
	v_mov_b64_e32 v[30:31], v[198:199]
	v_pk_mul_f32 v[24:25], v[24:25], v[28:29]
	s_nop 0
	v_cvt_pk_bf16_f32 v28, v24, v25
	v_mul_f32_e32 v24, 0x41800000, v24
	v_mul_f32_e32 v25, 0x41800000, v25
	v_cvt_pk_fp8_f32 v32, v24, v25
	v_pk_mul_f32 v[26:27], v[26:27], v[30:31]
	s_nop 0
	v_cvt_pk_bf16_f32 v29, v26, v27
	v_mul_f32_e32 v26, 0x41800000, v26
	v_mul_f32_e32 v27, 0x41800000, v27
	v_cvt_pk_fp8_f32 v32, v26, v27 op_sel:[0,0,1]
	global_store_dwordx2 v[74:75], v[28:29], off offset:512
	v_mov_b32_e32 v28, 0
	global_store_dword v[76:77], v32, off offset:2304
	v_mov_b64_e32 v[24:25], v[200:201]
	v_mov_b64_e32 v[26:27], v[202:203]
	v_pk_mul_f32 v[20:21], v[20:21], v[24:25]
	s_nop 0
	v_cvt_pk_bf16_f32 v24, v20, v21
	v_mul_f32_e32 v20, 0x41800000, v20
	v_mul_f32_e32 v21, 0x41800000, v21
	v_cvt_pk_fp8_f32 v28, v20, v21
	v_pk_mul_f32 v[22:23], v[22:23], v[26:27]
	v_mov_b32_e32 v26, 0
	v_cvt_pk_bf16_f32 v25, v22, v23
	v_mul_f32_e32 v22, 0x41800000, v22
	v_mul_f32_e32 v23, 0x41800000, v23
	v_cvt_pk_fp8_f32 v28, v22, v23 op_sel:[0,0,1]
	global_store_dwordx2 v[74:75], v[24:25], off offset:1024
	v_add_co_u32_e32 v24, vcc, s9, v72
	global_store_dword v[76:77], v28, off offset:2560
	v_mov_b64_e32 v[20:21], v[204:205]
	v_mov_b64_e32 v[22:23], v[206:207]
	v_addc_co_u32_e32 v25, vcc, 0, v73, vcc
	v_pk_mul_f32 v[16:17], v[16:17], v[20:21]
	s_nop 0
	v_cvt_pk_bf16_f32 v20, v16, v17
	v_mul_f32_e32 v16, 0x41800000, v16
	v_mul_f32_e32 v17, 0x41800000, v17
	v_cvt_pk_fp8_f32 v26, v16, v17
	v_pk_mul_f32 v[18:19], v[18:19], v[22:23]
	s_nop 0
	v_cvt_pk_bf16_f32 v21, v18, v19
	v_mul_f32_e32 v18, 0x41800000, v18
	v_mul_f32_e32 v19, 0x41800000, v19
	v_cvt_pk_fp8_f32 v26, v18, v19 op_sel:[0,0,1]
	global_store_dwordx2 v[74:75], v[20:21], off offset:1536
	v_mov_b32_e32 v20, 0
	global_store_dword v[76:77], v26, off offset:2816
	v_mov_b64_e32 v[16:17], v[208:209]
	v_mov_b64_e32 v[18:19], v[210:211]
	v_pk_mul_f32 v[12:13], v[12:13], v[16:17]
	s_nop 0
	v_cvt_pk_bf16_f32 v16, v12, v13
	v_mul_f32_e32 v12, 0x41800000, v12
	v_mul_f32_e32 v13, 0x41800000, v13
	v_cvt_pk_fp8_f32 v20, v12, v13
	v_pk_mul_f32 v[14:15], v[14:15], v[18:19]
	s_nop 0
	v_cvt_pk_bf16_f32 v17, v14, v15
	v_mul_f32_e32 v14, 0x41800000, v14
	v_mul_f32_e32 v15, 0x41800000, v15
	v_cvt_pk_fp8_f32 v20, v14, v15 op_sel:[0,0,1]
	global_store_dwordx2 v[74:75], v[16:17], off offset:2048
	v_mov_b32_e32 v16, 0
	global_store_dword v[76:77], v20, off offset:3072
	v_mov_b64_e32 v[12:13], v[212:213]
	v_mov_b64_e32 v[14:15], v[214:215]
	v_pk_mul_f32 v[8:9], v[8:9], v[12:13]
	s_nop 0
	v_cvt_pk_bf16_f32 v12, v8, v9
	v_mul_f32_e32 v8, 0x41800000, v8
	v_mul_f32_e32 v9, 0x41800000, v9
	v_cvt_pk_fp8_f32 v16, v8, v9
	v_pk_mul_f32 v[10:11], v[10:11], v[14:15]
	s_nop 0
	v_cvt_pk_bf16_f32 v13, v10, v11
	v_mul_f32_e32 v10, 0x41800000, v10
	v_mul_f32_e32 v11, 0x41800000, v11
	v_cvt_pk_fp8_f32 v16, v10, v11 op_sel:[0,0,1]
	global_store_dwordx2 v[74:75], v[12:13], off offset:2560
	v_mov_b32_e32 v12, 0
	global_store_dword v[76:77], v16, off offset:3328
	v_mov_b64_e32 v[8:9], v[216:217]
	v_mov_b64_e32 v[10:11], v[218:219]
	v_pk_mul_f32 v[4:5], v[4:5], v[8:9]
	s_nop 0
	v_cvt_pk_bf16_f32 v8, v4, v5
	v_mul_f32_e32 v4, 0x41800000, v4
	v_mul_f32_e32 v5, 0x41800000, v5
	v_cvt_pk_fp8_f32 v12, v4, v5
	v_pk_mul_f32 v[6:7], v[6:7], v[10:11]
	s_nop 0
	v_mul_f32_e32 v4, 0x41800000, v6
	v_mul_f32_e32 v5, 0x41800000, v7
	v_cvt_pk_fp8_f32 v12, v4, v5 op_sel:[0,0,1]
	v_cvt_pk_bf16_f32 v9, v6, v7
	global_store_dwordx2 v[74:75], v[8:9], off offset:3072
	global_store_dword v[76:77], v12, off offset:3584
	v_mov_b64_e32 v[4:5], v[220:221]
	v_mov_b64_e32 v[6:7], v[222:223]
	v_mov_b32_e32 v8, 0
	v_pk_mul_f32 v[0:1], v[0:1], v[4:5]
	s_nop 0
	v_mul_f32_e32 v4, 0x41800000, v0
	v_mul_f32_e32 v5, 0x41800000, v1
	v_cvt_pk_fp8_f32 v8, v4, v5
	v_pk_mul_f32 v[2:3], v[2:3], v[6:7]
	v_cvt_pk_bf16_f32 v0, v0, v1
	s_nop 0
	v_mul_f32_e32 v4, 0x41800000, v2
	v_mul_f32_e32 v5, 0x41800000, v3
	v_cvt_pk_fp8_f32 v8, v4, v5 op_sel:[0,0,1]
	v_cvt_pk_bf16_f32 v1, v2, v3
	global_store_dwordx2 v[74:75], v[0:1], off offset:3584
	global_store_dword v[76:77], v8, off offset:3840
	s_cbranch_scc0 .LBB0_29
